# B0 item: compiler IEEE f32 division sequences (11 instr) replaced by v_rcp_f32 + v_mul_f32 (f32, 1.5 ulp), on top of hand-written phase A part 1 and two-round-trip LoRA fragment loads
# speedup vs baseline: 1.0134x; 1.0134x over previous
.LBB0_483:
	s_andn2_saveexec_b64 s[10:11], s[10:11]
	s_cbranch_execz .LBB0_485
	s_waitcnt vmcnt(0)
	v_add_f32_e32 v2, v2, v2
	v_mul_f32_e32 v2, 0x3fb8aa3b, v2
	v_exp_f32_e32 v2, v2
	s_nop 0
	v_add_f32_e32 v2, 1.0, v2
	s_nop 7
	v_rcp_f32_e32 v3, v2
	s_nop 0
	v_mul_f32_e32 v2, 2.0, v3
	v_sub_f32_e32 v2, 1.0, v2
	v_cvt_pk_bf16_f32 v2, v2, v131
	ds_write_b16 v234, v2

.LBB0_487:
	s_andn2_saveexec_b64 s[10:11], s[10:11]
	s_cbranch_execz .LBB0_489
	s_waitcnt vmcnt(0)
	v_add_f32_e32 v2, v2, v2
	v_mul_f32_e32 v2, 0x3fb8aa3b, v2
	v_exp_f32_e32 v2, v2
	s_nop 0
	v_add_f32_e32 v2, 1.0, v2
	s_nop 7
	v_rcp_f32_e32 v3, v2
	s_nop 0
	v_mul_f32_e32 v2, 2.0, v3
	v_sub_f32_e32 v2, 1.0, v2
	v_cvt_pk_bf16_f32 v2, v2, v131
	ds_write_b16 v235, v2

.LBB0_491:
	s_andn2_saveexec_b64 s[10:11], s[10:11]
	s_cbranch_execz .LBB0_493
	s_waitcnt vmcnt(0)
	v_add_f32_e32 v2, v2, v2
	v_mul_f32_e32 v2, 0x3fb8aa3b, v2
	v_exp_f32_e32 v2, v2
	s_nop 0
	v_add_f32_e32 v2, 1.0, v2
	s_nop 7
	v_rcp_f32_e32 v3, v2
	s_nop 0
	v_mul_f32_e32 v2, 2.0, v3
	v_sub_f32_e32 v2, 1.0, v2
	v_cvt_pk_bf16_f32 v2, v2, v131
	ds_write_b16 v236, v2

.LBB0_495:
	s_andn2_saveexec_b64 s[10:11], s[10:11]
	s_cbranch_execz .LBB0_497
	s_waitcnt vmcnt(0)
	v_add_f32_e32 v2, v2, v2
	v_mul_f32_e32 v2, 0x3fb8aa3b, v2
	v_exp_f32_e32 v2, v2
	s_nop 0
	v_add_f32_e32 v2, 1.0, v2
	s_nop 7
	v_rcp_f32_e32 v3, v2
	s_nop 0
	v_mul_f32_e32 v2, 2.0, v3
	v_sub_f32_e32 v2, 1.0, v2
	v_cvt_pk_bf16_f32 v2, v2, v131
	ds_write_b16 v237, v2

.LBB0_499:
	s_andn2_saveexec_b64 s[10:11], s[10:11]
	s_cbranch_execz .LBB0_501
	s_waitcnt vmcnt(0)
	v_add_f32_e32 v2, v2, v2
	v_mul_f32_e32 v2, 0x3fb8aa3b, v2
	v_exp_f32_e32 v2, v2
	s_nop 0
	v_add_f32_e32 v2, 1.0, v2
	s_nop 7
	v_rcp_f32_e32 v3, v2
	s_nop 0
	v_mul_f32_e32 v2, 2.0, v3
	v_sub_f32_e32 v2, 1.0, v2
	v_cvt_pk_bf16_f32 v2, v2, v131
	ds_write_b16 v238, v2

.LBB0_503:
	s_andn2_saveexec_b64 s[10:11], s[10:11]
	s_cbranch_execz .LBB0_505
	s_waitcnt vmcnt(0)
	v_add_f32_e32 v2, v2, v2
	v_mul_f32_e32 v2, 0x3fb8aa3b, v2
	v_exp_f32_e32 v2, v2
	s_nop 0
	v_add_f32_e32 v2, 1.0, v2
	s_nop 7
	v_rcp_f32_e32 v3, v2
	s_nop 0
	v_mul_f32_e32 v2, 2.0, v3
	v_sub_f32_e32 v2, 1.0, v2
	v_cvt_pk_bf16_f32 v2, v2, v131
	ds_write_b16 v239, v2

.LBB0_507:
	s_andn2_saveexec_b64 s[10:11], s[10:11]
	s_cbranch_execz .LBB0_509
	s_waitcnt vmcnt(0)
	v_add_f32_e32 v2, v2, v2
	v_mul_f32_e32 v2, 0x3fb8aa3b, v2
	v_exp_f32_e32 v2, v2
	s_nop 0
	v_add_f32_e32 v2, 1.0, v2
	s_nop 7
	v_rcp_f32_e32 v3, v2
	s_nop 0
	v_mul_f32_e32 v2, 2.0, v3
	v_sub_f32_e32 v2, 1.0, v2
	v_cvt_pk_bf16_f32 v2, v2, v131
	ds_write_b16 v240, v2

.LBB0_511:
	s_andn2_saveexec_b64 s[10:11], s[10:11]
	s_cbranch_execz .LBB0_513
	s_waitcnt vmcnt(0)
	v_add_f32_e32 v2, v2, v2
	v_mul_f32_e32 v2, 0x3fb8aa3b, v2
	v_exp_f32_e32 v2, v2
	s_nop 0
	v_add_f32_e32 v2, 1.0, v2
	s_nop 7
	v_rcp_f32_e32 v3, v2
	s_nop 0
	v_mul_f32_e32 v2, 2.0, v3
	v_sub_f32_e32 v2, 1.0, v2
	v_cvt_pk_bf16_f32 v2, v2, v131
	ds_write_b16 v241, v2
.LBB0_513:
	s_or_b64 exec, exec, s[10:11]
	s_waitcnt lgkmcnt(0)
	s_barrier
	ds_read_b128 v[192:195], v101
	ds_read_b128 v[196:199], v101 offset:64
	ds_read_b128 v[244:247], v101 offset:4608
	ds_read_b128 v[248:251], v101 offset:4672
	global_load_dwordx4 v[94:97], v[102:103], off
	global_load_dwordx4 v[82:85], v[104:105], off
	global_load_dwordx4 v[90:93], v[106:107], off
	global_load_dwordx4 v[62:65], v[112:113], off
	global_load_dwordx4 v[18:21], v[126:127], off
	global_load_dwordx4 v[70:73], v[110:111], off
	global_load_dwordx4 v[42:45], v[118:119], off
	global_load_dwordx4 v[34:37], v[120:121], off
	global_load_dwordx4 v[2:5], v[128:129], off
	global_load_dwordx4 v[50:53], v[108:109], off
	global_load_dwordx4 v[38:41], v[122:123], off
	global_load_dwordx4 v[66:69], v[114:115], off
	global_load_dwordx4 v[30:33], v[124:125], off
	global_load_dwordx4 v[58:61], v[116:117], off
	global_load_dwordx4 v[14:17], v[136:137], off
	global_load_dwordx4 v[6:9], v[138:139], off
	global_load_dwordx4 v[22:25], v[102:103], off offset:64
	global_load_dwordx4 v[26:29], v[140:141], off
	global_load_dwordx4 v[46:49], v[142:143], off
	global_load_dwordx4 v[54:57], v[146:147], off
	global_load_dwordx4 v[74:77], v[126:127], off offset:64
	global_load_dwordx4 v[78:81], v[110:111], off offset:64
	global_load_dwordx4 v[86:89], v[118:119], off offset:64
	global_load_dwordx4 v[186:189], v[152:153], off
	v_or_b32_e32 v243, v10, v1
	v_cmp_gt_i32_e32 vcc, s37, v243
	v_cndmask_b32_e32 v11, v213, v214, vcc
	s_waitcnt lgkmcnt(0)
	s_waitcnt vmcnt(23)
	v_mfma_f32_16x16x32_bf16 v[94:97], v[94:97], v[192:195], 0
	s_waitcnt vmcnt(22)
	v_mfma_f32_16x16x32_bf16 v[82:85], v[82:85], v[192:195], 0
	s_waitcnt vmcnt(21)
	v_mfma_f32_16x16x32_bf16 v[90:93], v[90:93], v[244:247], 0
	s_waitcnt vmcnt(20)
	v_mfma_f32_16x16x32_bf16 v[62:65], v[62:65], v[192:195], 0
	s_waitcnt vmcnt(19)
	v_mfma_f32_16x16x32_bf16 v[18:21], v[18:21], v[192:195], 0
	s_waitcnt vmcnt(18)
	v_mfma_f32_16x16x32_bf16 v[70:73], v[70:73], v[192:195], 0
	s_waitcnt vmcnt(17)
	v_mfma_f32_16x16x32_bf16 v[42:45], v[42:45], v[192:195], 0
	s_waitcnt vmcnt(16)
	v_mfma_f32_16x16x32_bf16 v[34:37], v[34:37], v[192:195], 0
	s_waitcnt vmcnt(15)
	v_mfma_f32_16x16x32_bf16 v[2:5], v[2:5], v[192:195], 0
	s_waitcnt vmcnt(14)
	v_mfma_f32_16x16x32_bf16 v[50:53], v[50:53], v[244:247], 0
	s_waitcnt vmcnt(13)
	v_mfma_f32_16x16x32_bf16 v[38:41], v[38:41], v[244:247], 0
	s_waitcnt vmcnt(12)
	v_mfma_f32_16x16x32_bf16 v[66:69], v[66:69], v[244:247], 0
	s_waitcnt vmcnt(11)
	v_mfma_f32_16x16x32_bf16 v[30:33], v[30:33], v[244:247], 0
	s_waitcnt vmcnt(10)
	v_mfma_f32_16x16x32_bf16 v[58:61], v[58:61], v[244:247], 0
	s_waitcnt vmcnt(9)
	v_mfma_f32_16x16x32_bf16 v[14:17], v[14:17], v[244:247], 0
	s_waitcnt vmcnt(8)
	v_mfma_f32_16x16x32_bf16 v[6:9], v[6:9], v[244:247], 0
	s_waitcnt vmcnt(7)
	v_mfma_f32_16x16x32_bf16 v[94:97], v[22:25], v[196:199], v[94:97]
	global_load_dwordx4 v[22:25], v[158:159], off
	s_waitcnt vmcnt(7)
	v_mfma_f32_16x16x32_bf16 v[82:85], v[26:29], v[196:199], v[82:85]
	global_load_dwordx4 v[26:29], v[144:145], off
	s_waitcnt vmcnt(7)
	v_mfma_f32_16x16x32_bf16 v[90:93], v[46:49], v[248:251], v[90:93]
	global_load_dwordx4 v[46:49], v[154:155], off
	s_waitcnt vmcnt(7)
	v_mfma_f32_16x16x32_bf16 v[62:65], v[54:57], v[196:199], v[62:65]
	global_load_dwordx4 v[54:57], v[148:149], off
	s_waitcnt vmcnt(7)
	v_mfma_f32_16x16x32_bf16 v[18:21], v[74:77], v[196:199], v[18:21]
	global_load_dwordx4 v[74:77], v[156:157], off
	s_waitcnt vmcnt(7)
	v_mfma_f32_16x16x32_bf16 v[70:73], v[78:81], v[196:199], v[70:73]
	global_load_dwordx4 v[78:81], v[150:151], off
	s_waitcnt vmcnt(7)
	v_mfma_f32_16x16x32_bf16 v[42:45], v[86:89], v[196:199], v[42:45]
	global_load_dwordx4 v[86:89], v[160:161], off
	s_waitcnt vmcnt(7)
	v_mfma_f32_16x16x32_bf16 v[34:37], v[186:189], v[196:199], v[34:37]
	global_load_dwordx4 v[186:189], v[162:163], off
	s_waitcnt vmcnt(7)
	v_mfma_f32_16x16x32_bf16 v[2:5], v[22:25], v[196:199], v[2:5]
	s_waitcnt vmcnt(6)
	v_mfma_f32_16x16x32_bf16 v[50:53], v[26:29], v[248:251], v[50:53]
	s_waitcnt vmcnt(5)
	v_mfma_f32_16x16x32_bf16 v[38:41], v[46:49], v[248:251], v[38:41]
	s_waitcnt vmcnt(4)
	v_mfma_f32_16x16x32_bf16 v[66:69], v[54:57], v[248:251], v[66:69]
	s_waitcnt vmcnt(3)
	v_mfma_f32_16x16x32_bf16 v[30:33], v[74:77], v[248:251], v[30:33]
	s_waitcnt vmcnt(2)
	v_mfma_f32_16x16x32_bf16 v[58:61], v[78:81], v[248:251], v[58:61]
	s_waitcnt vmcnt(1)
	v_mfma_f32_16x16x32_bf16 v[14:17], v[86:89], v[248:251], v[14:17]
	s_waitcnt vmcnt(0)
	v_mfma_f32_16x16x32_bf16 v[6:9], v[186:189], v[248:251], v[6:9]
	v_cndmask_b32_e32 v12, v215, v216, vcc
	v_bitop3_b32 v130, v12, v10, v1 bitop3:0xe0
	v_mov_b64_e32 v[12:13], s[28:29]
	v_cndmask_b32_e64 v22, 10, 8, vcc
	v_and_b32_e32 v10, v11, v10
	v_mad_i64_i32 v[12:13], s[10:11], v243, s36, v[12:13]
	v_lshlrev_b64 v[22:23], v22, v[98:99]
	v_ashrrev_i32_e32 v11, 31, v10
	v_lshl_add_u64 v[22:23], v[22:23], 0, v[130:131]
	v_lshl_add_u64 v[190:191], v[12:13], 0, s[92:93]
	v_lshl_add_u64 v[204:205], v[10:11], 2, v[22:23]
	v_lshl_add_u64 v[10:11], v[190:191], 0, v[164:165]
	v_lshl_add_u64 v[188:189], v[12:13], 0, v[164:165]
	global_load_dwordx4 v[86:89], v[10:11], off
	global_load_dwordx4 v[46:49], v[188:189], off offset:3072
	flat_load_dwordx4 v[192:195], v[166:167]
	flat_load_dwordx4 v[196:199], v[166:167] offset:64
	global_load_dwordx4 v[54:57], v[188:189], off offset:3136
	global_load_dwordx4 v[26:29], v[188:189], off offset:3200
	flat_load_dwordx4 v[244:247], v[166:167] offset:128
	global_load_dwordx4 v[10:13], v[188:189], off offset:3264
	flat_load_dwordx4 v[248:251], v[166:167] offset:192
	global_load_dwordx4 v[74:77], v[188:189], off offset:2048
	flat_load_dwordx4 v[78:81], v[174:175]
	flat_load_dwordx4 v[22:25], v[176:177]
	v_mad_u64_u32 v[186:187], s[10:11], v204, s66, v[182:183]
	v_mad_i32_i24 v187, v205, s66, v187
	s_mov_b32 s10, 0x800000
	s_waitcnt vmcnt(0)
	global_store_dwordx4 v[186:187], v[86:89], off offset:512
	s_waitcnt lgkmcnt(0)
	s_nop 0
	v_pk_mul_f32 v[86:87], v[48:49], v[194:195]
	v_pk_mul_f32 v[224:225], v[46:47], v[192:193]
	v_pk_mul_f32 v[88:89], v[86:87], v[86:87]
	v_pk_mul_f32 v[192:193], v[224:225], v[224:225]
	v_pk_mul_f32 v[200:201], v[56:57], v[198:199]
	v_pk_mov_b32 v[194:195], v[192:193], v[88:89] op_sel:[1,0]
	v_mov_b32_e32 v193, v89
	v_pk_mul_f32 v[202:203], v[54:55], v[196:197]
	v_pk_add_f32 v[88:89], v[194:195], v[192:193]
	v_pk_mul_f32 v[192:193], v[200:201], v[200:201]
	v_pk_mul_f32 v[194:195], v[202:203], v[202:203]
	v_pk_mul_f32 v[198:199], v[26:27], v[244:245]
	v_pk_mov_b32 v[196:197], v[194:195], v[192:193] op_sel:[1,0]
	v_mov_b32_e32 v195, v193
	v_pk_add_f32 v[218:219], v[196:197], v[194:195]
	v_pk_mul_f32 v[194:195], v[10:11], v[248:249]
	v_pk_add_f32 v[88:89], v[88:89], v[88:89] op_sel:[0,1] op_sel_hi:[1,0]
	v_pk_add_f32 v[218:219], v[218:219], v[218:219] op_sel:[0,1] op_sel_hi:[1,0]
	v_pk_mul_f32 v[196:197], v[28:29], v[246:247]
	v_mul_f32_e32 v89, v194, v194
	v_mul_f32_e32 v219, v195, v195
	v_mul_f32_e32 v130, v199, v199
	v_pk_add_f32 v[88:89], v[88:89], v[218:219]
	v_pk_fma_f32 v[218:219], v[198:199], v[198:199], v[130:131] op_sel_hi:[1,1,0]
	v_mul_f32_e32 v130, v197, v197
	v_pk_mul_f32 v[192:193], v[12:13], v[250:251]
	v_pk_fma_f32 v[244:245], v[196:197], v[196:197], v[130:131] op_sel_hi:[1,1,0]
	v_mul_f32_e32 v219, v192, v192
	v_mul_f32_e32 v245, v193, v193
	v_pk_add_f32 v[218:219], v[218:219], v[244:245]
	v_xor_b32_e32 v130, 16, v217
	v_pk_add_f32 v[88:89], v[88:89], v[218:219]
	s_nop 0
	v_add_f32_e32 v88, v88, v89
	v_and_b32_e32 v89, 64, v217
	v_add_u32_e32 v89, 64, v89
	v_cmp_lt_i32_e32 vcc, v130, v89
	s_nop 1
	v_cndmask_b32_e32 v130, v217, v130, vcc
	v_lshlrev_b32_e32 v244, 2, v130
	ds_bpermute_b32 v130, v244, v88
	s_waitcnt lgkmcnt(0)
	v_add_f32_e32 v88, v88, v130
	v_xor_b32_e32 v130, 32, v217
	v_cmp_lt_i32_e32 vcc, v130, v89
	s_nop 1
	v_cndmask_b32_e32 v89, v217, v130, vcc
	v_lshlrev_b32_e32 v245, 2, v89
	ds_bpermute_b32 v89, v245, v88
	s_waitcnt lgkmcnt(0)
	v_add_f32_e32 v88, v88, v89
	v_add_f32_e32 v88, 0x2b8cbccc, v88
	v_mul_f32_e32 v89, 0x4b800000, v88
	v_cmp_gt_f32_e32 vcc, s10, v88
	s_nop 1
	v_cndmask_b32_e32 v88, v88, v89, vcc
	v_rsq_f32_e32 v88, v88
	s_nop 0
	v_mul_f32_e32 v89, 0x45800000, v88
	v_cndmask_b32_e32 v130, v88, v89, vcc
	v_pk_mul_f32 v[88:89], v[86:87], v[130:131] op_sel_hi:[1,0]
	v_pk_mul_f32 v[86:87], v[224:225], v[130:131] op_sel_hi:[1,0]
	global_store_dwordx4 v[186:187], v[74:77], off
	global_store_dwordx4 v[186:187], v[86:89], off offset:256
	ds_read_b128 v[246:249], v255
	s_waitcnt lgkmcnt(0)
	v_add_f32_e32 v218, v94, v246
	v_add_f32_e32 v219, v95, v247
	v_add_f32_e32 v224, v96, v248
	v_add_f32_e32 v96, v97, v249
	ds_read_b128 v[246:249], v255 offset:128
	v_mul_f32_e32 v97, 0xbfb8aa3b, v218
	v_exp_f32_e32 v97, v97
	v_mad_u64_u32 v[94:95], s[10:11], v204, s66, v[184:185]
	v_mad_i32_i24 v95, v205, s66, v95
	v_add_f32_e32 v97, 1.0, v97
	s_nop 1
	v_mul_f32_e32 v224, 0xbfb8aa3b, v224
	v_exp_f32_e32 v224, v224
	v_mul_f32_e32 v96, 0xbfb8aa3b, v96
	s_nop 3
	v_add_f32_e32 v224, 1.0, v224
	v_exp_f32_e32 v96, v96
	s_waitcnt lgkmcnt(0)
	v_add_f32_e32 v90, v90, v246
	s_nop 3
	v_mul_f32_e32 v205, 0xbfb8aa3b, v219
	v_exp_f32_e32 v205, v205
	v_add_f32_e32 v91, v91, v247
	v_mul_f32_e32 v90, 0xbfb8aa3b, v90
	v_mul_f32_e32 v91, 0xbfb8aa3b, v91
	v_add_f32_e32 v205, 1.0, v205
	s_nop 1
	v_exp_f32_e32 v90, v90
	v_exp_f32_e32 v91, v91
	v_add_f32_e32 v92, v92, v248
	s_nop 6
	v_pk_add_f32 v[90:91], v[90:91], 1.0 op_sel_hi:[1,0]
	s_nop 2
	v_add_f32_e32 v93, v93, v249
	v_add_f32_e32 v96, 1.0, v96
	v_rcp_f32_e32 v204, v97
	s_nop 0
	v_mul_f32_e32 v97, s45, v204
	s_nop 7
	v_mul_f32_e32 v97, 0x3fb8aa3b, v97
	v_rcp_f32_e32 v218, v205
	s_nop 0
	v_mul_f32_e32 v204, s45, v218
	v_mul_f32_e32 v204, 0x3fb8aa3b, v204
	s_nop 7
	s_nop 0
	s_nop 7
	s_nop 0
	s_nop 7
	v_exp_f32_e32 v246, v97
	v_rcp_f32_e32 v248, v224
	s_nop 0
	v_mul_f32_e32 v97, s45, v248
	v_rcp_f32_e32 v249, v96
	s_nop 0
	v_mul_f32_e32 v96, s45, v249
	v_mul_f32_e32 v97, 0x3fb8aa3b, v97
	v_mul_f32_e32 v96, 0x3fb8aa3b, v96
	v_exp_f32_e32 v248, v97
	v_exp_f32_e32 v249, v96
	v_rcp_f32_e32 v97, v91
	s_nop 0
	v_rcp_f32_e32 v96, v90
	s_nop 0
	v_mul_f32_e32 v90, 0xbfb8aa3b, v92
	v_mul_f32_e32 v91, 0xbfb8aa3b, v93
	v_exp_f32_e32 v90, v90
	v_exp_f32_e32 v91, v91
	v_exp_f32_e32 v247, v204
	v_pk_add_f32 v[90:91], v[90:91], 1.0 op_sel_hi:[1,0]
	s_nop 0
	s_nop 1
	global_store_dwordx4 v[94:95], v[246:249], off
	s_nop 7
	s_nop 0
	s_nop 7
	v_rcp_f32_e32 v205, v91
	s_nop 0
	v_rcp_f32_e32 v204, v90
	s_nop 0
	v_xor_b32_e32 v91, 0x80000000, v97
	v_xor_b32_e32 v90, 0x80000000, v96
	v_xor_b32_e32 v93, 0x80000000, v205
	v_xor_b32_e32 v92, 0x80000000, v204
	v_pk_mul_f32 v[92:93], v[88:89], v[92:93]
	v_pk_mul_f32 v[90:91], v[86:87], v[90:91]
	global_store_dwordx4 v[94:95], v[90:93], off offset:256
	s_nop 1
	v_pk_add_f32 v[90:91], v[96:97], -1.0 op_sel_hi:[1,0]
	v_pk_add_f32 v[92:93], v[204:205], -1.0 op_sel_hi:[1,0]
	v_pk_fma_f32 v[90:91], v[78:79], v[90:91], 1.0 op_sel_hi:[1,1,0]
	v_pk_fma_f32 v[92:93], v[80:81], v[92:93], 1.0 op_sel_hi:[1,1,0]
	v_pk_mul_f32 v[90:91], v[46:47], v[90:91]
	v_pk_mul_f32 v[92:93], v[48:49], v[92:93]
	global_store_dwordx4 v[94:95], v[90:93], off offset:512
	ds_read_b128 v[246:249], v255 offset:64
	s_waitcnt lgkmcnt(0)
	v_add_f32_e32 v96, v82, v246
	v_add_f32_e32 v97, v83, v247
	v_add_f32_e32 v204, v84, v248
	v_add_f32_e32 v205, v85, v249
	ds_read_b128 v[82:85], v255 offset:192
	s_waitcnt lgkmcnt(0)
	v_add_f32_e32 v50, v50, v82
	v_mul_f32_e32 v82, 0xbfb8aa3b, v96
	v_exp_f32_e32 v82, v82
	v_add_f32_e32 v52, v52, v84
	v_add_f32_e32 v51, v51, v83
	v_add_f32_e32 v53, v53, v85
	v_add_f32_e32 v84, 1.0, v82
	s_nop 1
	v_mul_f32_e32 v50, 0xbfb8aa3b, v50
	v_mul_f32_e32 v51, 0xbfb8aa3b, v51
	v_exp_f32_e32 v50, v50
	s_nop 7
	v_mul_f32_e32 v82, 0xbfb8aa3b, v97
	v_exp_f32_e32 v82, v82
	v_exp_f32_e32 v51, v51
	v_mul_f32_e32 v52, 0xbfb8aa3b, v52
	v_mul_f32_e32 v53, 0xbfb8aa3b, v53
	v_add_f32_e32 v96, 1.0, v82
	s_nop 1
	v_pk_add_f32 v[50:51], v[50:51], 1.0 op_sel_hi:[1,0]
	v_exp_f32_e32 v52, v52
	v_exp_f32_e32 v53, v53
	s_nop 7
	v_pk_add_f32 v[52:53], v[52:53], 1.0 op_sel_hi:[1,0]
	s_nop 7
	v_rcp_f32_e32 v51, v51
	s_nop 0
	v_mul_f32_e32 v82, 0xbfb8aa3b, v204
	v_exp_f32_e32 v82, v82
	s_nop 6
	v_add_f32_e32 v204, 1.0, v82
	s_nop 1
	v_rcp_f32_e32 v50, v50
	s_nop 0
	s_nop 0
	s_nop 0
	s_nop 7
	v_mul_f32_e32 v82, 0xbfb8aa3b, v205
	v_exp_f32_e32 v82, v82
	s_nop 0
	v_add_f32_e32 v205, 1.0, v82
	s_nop 1
	s_nop 0
	s_nop 7
	s_nop 0
	s_nop 7
	v_rcp_f32_e32 v53, v53
	s_nop 0
	s_mov_b32 s10, 0x1800000
	s_nop 7
	v_rcp_f32_e32 v52, v52
	s_nop 0
	v_pk_add_f32 v[82:83], v[50:51], -1.0 op_sel_hi:[1,0]
	v_xor_b32_e32 v51, 0x80000000, v51
	v_pk_fma_f32 v[78:79], v[78:79], v[82:83], 1.0 op_sel_hi:[1,1,0]
	v_pk_add_f32 v[82:83], v[52:53], -1.0 op_sel_hi:[1,0]
	v_pk_mul_f32 v[46:47], v[46:47], v[78:79]
	v_pk_fma_f32 v[80:81], v[80:81], v[82:83], 1.0 op_sel_hi:[1,1,0]
	v_rcp_f32_e32 v85, v84
	s_nop 0
	v_mul_f32_e32 v78, s45, v85
	v_pk_mul_f32 v[48:49], v[48:49], v[80:81]
	v_rcp_f32_e32 v97, v96
	s_nop 0
	v_mul_f32_e32 v79, s45, v97
	v_rcp_f32_e32 v218, v204
	s_nop 0
	v_mul_f32_e32 v80, s45, v218
	v_rcp_f32_e32 v219, v205
	s_nop 0
	v_mul_f32_e32 v81, s45, v219
	v_mul_f32_e32 v78, 0x3fb8aa3b, v78
	v_mul_f32_e32 v79, 0x3fb8aa3b, v79
	v_mul_f32_e32 v80, 0x3fb8aa3b, v80
	v_mul_f32_e32 v81, 0x3fb8aa3b, v81
	v_exp_f32_e32 v78, v78
	v_exp_f32_e32 v79, v79
	v_exp_f32_e32 v80, v80
	v_exp_f32_e32 v81, v81
	v_add_co_u32_e32 v82, vcc, s10, v94
	v_xor_b32_e32 v50, 0x80000000, v50
	v_xor_b32_e32 v53, 0x80000000, v53
	v_xor_b32_e32 v52, 0x80000000, v52
	v_addc_co_u32_e32 v83, vcc, 0, v95, vcc
	v_pk_mul_f32 v[52:53], v[88:89], v[52:53]
	v_pk_mul_f32 v[50:51], v[86:87], v[50:51]
	global_store_dwordx4 v[82:83], v[78:81], off
	global_store_dwordx4 v[82:83], v[50:53], off offset:256
	v_mul_f32_e32 v88, v74, v46
	v_mul_f32_e32 v89, v75, v47
	global_store_dwordx4 v[82:83], v[46:49], off offset:512
	v_mul_f32_e32 v84, v74, v90
	v_mul_f32_e32 v85, v75, v91
	v_lshl_add_u64 v[46:47], v[168:169], 2, v[190:191]
	v_mul_f32_e32 v86, v76, v92
	v_mul_f32_e32 v87, v77, v93
	v_mul_f32_e32 v90, v76, v48
	v_mul_f32_e32 v91, v77, v49
	global_load_dwordx4 v[74:77], v[46:47], off
	s_nop 0
	global_load_dwordx4 v[46:49], v[188:189], off offset:2112
	flat_load_dwordx4 v[78:81], v[174:175] offset:64
	flat_load_dwordx4 v[50:53], v[176:177] offset:64
	s_waitcnt vmcnt(0)
	global_store_dwordx4 v[186:187], v[74:77], off offset:576
	s_nop 1
	v_pk_mul_f32 v[76:77], v[200:201], v[130:131] op_sel_hi:[1,0]
	v_pk_mul_f32 v[74:75], v[202:203], v[130:131] op_sel_hi:[1,0]
	global_store_dwordx4 v[186:187], v[46:49], off offset:64
	global_store_dwordx4 v[186:187], v[74:77], off offset:320
	ds_read_b128 v[200:203], v255 offset:16
	s_waitcnt lgkmcnt(0)
	v_add_f32_e32 v92, v70, v200
	v_add_f32_e32 v93, v71, v201
	v_add_f32_e32 v96, v72, v202
	v_add_f32_e32 v97, v73, v203
	ds_read_b128 v[70:73], v255 offset:144
	s_waitcnt lgkmcnt(0)
	v_add_f32_e32 v72, v68, v72
	v_mul_f32_e32 v68, 0xbfb8aa3b, v92
	v_exp_f32_e32 v68, v68
	v_add_f32_e32 v73, v69, v73
	v_add_f32_e32 v66, v66, v70
	v_add_f32_e32 v67, v67, v71
	v_add_f32_e32 v68, 1.0, v68
	s_nop 1
	v_mul_f32_e32 v66, 0xbfb8aa3b, v66
	v_mul_f32_e32 v67, 0xbfb8aa3b, v67
	v_exp_f32_e32 v66, v66
	s_nop 7
	v_mul_f32_e32 v70, 0xbfb8aa3b, v93
	v_exp_f32_e32 v70, v70
	v_exp_f32_e32 v67, v67
	v_add_f32_e32 v92, 1.0, v70
	s_nop 1
	s_nop 0
	s_nop 7
	v_pk_add_f32 v[70:71], v[66:67], 1.0 op_sel_hi:[1,0]
	s_nop 0
	s_nop 1
	s_nop 0
	s_nop 7
	v_rcp_f32_e32 v71, v71
	s_nop 0
	s_nop 7
	v_mul_f32_e32 v66, 0xbfb8aa3b, v96
	v_exp_f32_e32 v66, v66
	v_rcp_f32_e32 v70, v70
	s_nop 0
	v_add_f32_e32 v96, 1.0, v66
	s_nop 1
	s_nop 0
	s_nop 7
	v_mul_f32_e32 v66, 0xbfb8aa3b, v97
	v_exp_f32_e32 v66, v66
	s_nop 0
	v_add_f32_e32 v97, 1.0, v66
	s_nop 1
	s_nop 0
	s_nop 7
	v_rcp_f32_e32 v69, v68
	s_nop 0
	v_mul_f32_e32 v66, s45, v69
	v_rcp_f32_e32 v93, v92
	s_nop 0
	v_mul_f32_e32 v67, s45, v93
	v_rcp_f32_e32 v202, v96
	s_nop 0
	v_mul_f32_e32 v68, s45, v202
	v_rcp_f32_e32 v203, v97
	s_nop 0
	v_mul_f32_e32 v69, s45, v203
	v_mul_f32_e32 v66, 0x3fb8aa3b, v66
	v_mul_f32_e32 v67, 0x3fb8aa3b, v67
	v_mul_f32_e32 v68, 0x3fb8aa3b, v68
	v_mul_f32_e32 v69, 0x3fb8aa3b, v69
	v_exp_f32_e32 v66, v66
	v_exp_f32_e32 v67, v67
	v_exp_f32_e32 v68, v68
	v_exp_f32_e32 v69, v69
	global_store_dwordx4 v[94:95], v[66:69], off offset:64
	s_nop 1
	v_mul_f32_e32 v66, 0xbfb8aa3b, v72
	v_mul_f32_e32 v67, 0xbfb8aa3b, v73
	v_exp_f32_e32 v66, v66
	v_exp_f32_e32 v67, v67
	s_nop 0
	v_pk_add_f32 v[66:67], v[66:67], 1.0 op_sel_hi:[1,0]
	s_nop 0
	s_nop 1
	s_nop 0
	s_nop 7
	s_nop 0
	s_nop 7
	v_rcp_f32_e32 v73, v67
	s_nop 0
	v_rcp_f32_e32 v72, v66
	s_nop 0
	v_xor_b32_e32 v67, 0x80000000, v71
	v_xor_b32_e32 v66, 0x80000000, v70
	v_xor_b32_e32 v69, 0x80000000, v73
	v_xor_b32_e32 v68, 0x80000000, v72
	v_pk_mul_f32 v[68:69], v[76:77], v[68:69]
	v_pk_mul_f32 v[66:67], v[74:75], v[66:67]
	global_store_dwordx4 v[94:95], v[66:69], off offset:320
	s_nop 1
	v_pk_add_f32 v[66:67], v[70:71], -1.0 op_sel_hi:[1,0]
	v_pk_add_f32 v[68:69], v[72:73], -1.0 op_sel_hi:[1,0]
	v_pk_fma_f32 v[66:67], v[78:79], v[66:67], 1.0 op_sel_hi:[1,1,0]
	v_pk_fma_f32 v[68:69], v[80:81], v[68:69], 1.0 op_sel_hi:[1,1,0]
	v_pk_mul_f32 v[66:67], v[54:55], v[66:67]
	v_pk_mul_f32 v[68:69], v[56:57], v[68:69]
	global_store_dwordx4 v[94:95], v[66:69], off offset:576
	ds_read_b128 v[70:73], v255 offset:80
	s_waitcnt lgkmcnt(0)
	v_add_f32_e32 v70, v62, v70
	v_add_f32_e32 v71, v63, v71
	v_add_f32_e32 v72, v64, v72
	v_add_f32_e32 v73, v65, v73
	ds_read_b128 v[62:65], v255 offset:208
	s_waitcnt lgkmcnt(0)
	v_add_f32_e32 v58, v58, v62
	v_mul_f32_e32 v62, 0xbfb8aa3b, v70
	v_exp_f32_e32 v62, v62
	v_add_f32_e32 v59, v59, v63
	v_add_f32_e32 v60, v60, v64
	v_add_f32_e32 v61, v61, v65
	v_add_f32_e32 v70, 1.0, v62
	s_nop 1
	v_mul_f32_e32 v58, 0xbfb8aa3b, v58
	v_mul_f32_e32 v59, 0xbfb8aa3b, v59
	v_exp_f32_e32 v58, v58
	s_nop 7
	v_mul_f32_e32 v62, 0xbfb8aa3b, v71
	v_exp_f32_e32 v62, v62
	v_exp_f32_e32 v59, v59
	v_mul_f32_e32 v60, 0xbfb8aa3b, v60
	v_mul_f32_e32 v61, 0xbfb8aa3b, v61
	v_add_f32_e32 v71, 1.0, v62
	s_nop 1
	v_pk_add_f32 v[58:59], v[58:59], 1.0 op_sel_hi:[1,0]
	v_exp_f32_e32 v60, v60
	v_exp_f32_e32 v61, v61
	s_nop 7
	v_pk_add_f32 v[60:61], v[60:61], 1.0 op_sel_hi:[1,0]
	s_nop 7
	v_rcp_f32_e32 v59, v59
	s_nop 0
	v_mul_f32_e32 v62, 0xbfb8aa3b, v72
	v_exp_f32_e32 v62, v62
	s_nop 6
	v_add_f32_e32 v72, 1.0, v62
	s_nop 1
	v_rcp_f32_e32 v58, v58
	s_nop 0
	s_nop 0
	s_nop 0
	s_nop 7
	v_mul_f32_e32 v62, 0xbfb8aa3b, v73
	v_exp_f32_e32 v62, v62
	s_nop 0
	v_add_f32_e32 v73, 1.0, v62
	s_nop 1
	s_nop 0
	s_nop 7
	s_nop 0
	s_nop 7
	v_rcp_f32_e32 v61, v61
	s_nop 0
	s_nop 7
	v_rcp_f32_e32 v60, v60
	s_nop 0
	v_pk_add_f32 v[62:63], v[58:59], -1.0 op_sel_hi:[1,0]
	v_pk_add_f32 v[64:65], v[60:61], -1.0 op_sel_hi:[1,0]
	v_pk_fma_f32 v[62:63], v[78:79], v[62:63], 1.0 op_sel_hi:[1,1,0]
	v_pk_fma_f32 v[64:65], v[80:81], v[64:65], 1.0 op_sel_hi:[1,1,0]
	v_pk_mul_f32 v[54:55], v[54:55], v[62:63]
	v_pk_mul_f32 v[56:57], v[56:57], v[64:65]
	v_rcp_f32_e32 v92, v70
	s_nop 0
	v_mul_f32_e32 v62, s45, v92
	v_rcp_f32_e32 v93, v71
	s_nop 0
	v_mul_f32_e32 v63, s45, v93
	v_rcp_f32_e32 v96, v72
	s_nop 0
	v_mul_f32_e32 v64, s45, v96
	v_rcp_f32_e32 v97, v73
	s_nop 0
	v_mul_f32_e32 v65, s45, v97
	v_mul_f32_e32 v62, 0x3fb8aa3b, v62
	v_mul_f32_e32 v63, 0x3fb8aa3b, v63
	v_mul_f32_e32 v64, 0x3fb8aa3b, v64
	v_mul_f32_e32 v65, 0x3fb8aa3b, v65
	v_exp_f32_e32 v62, v62
	v_exp_f32_e32 v63, v63
	v_exp_f32_e32 v64, v64
	v_exp_f32_e32 v65, v65
	v_xor_b32_e32 v59, 0x80000000, v59
	v_xor_b32_e32 v58, 0x80000000, v58
	v_xor_b32_e32 v61, 0x80000000, v61
	v_xor_b32_e32 v60, 0x80000000, v60
	v_pk_mul_f32 v[58:59], v[74:75], v[58:59]
	v_pk_mul_f32 v[60:61], v[76:77], v[60:61]
	global_store_dwordx4 v[82:83], v[62:65], off offset:64
	global_store_dwordx4 v[82:83], v[58:61], off offset:320
	global_store_dwordx4 v[82:83], v[54:57], off offset:576
	s_nop 0
	v_lshl_add_u64 v[58:59], v[170:171], 2, v[190:191]
	global_load_dwordx4 v[70:73], v[58:59], off
	s_nop 0
	global_load_dwordx4 v[58:61], v[188:189], off offset:2176
	flat_load_dwordx4 v[74:77], v[174:175] offset:128
	flat_load_dwordx4 v[62:65], v[176:177] offset:128
	s_waitcnt vmcnt(0)
	global_store_dwordx4 v[186:187], v[70:73], off offset:640
	s_nop 1
	v_pk_mul_f32 v[72:73], v[196:197], v[130:131] op_sel_hi:[1,0]
	v_pk_mul_f32 v[70:71], v[198:199], v[130:131] op_sel_hi:[1,0]
	global_store_dwordx4 v[186:187], v[58:61], off offset:128
	global_store_dwordx4 v[186:187], v[70:73], off offset:384
	ds_read_b128 v[78:81], v255 offset:32
	s_waitcnt lgkmcnt(0)
	v_add_f32_e32 v78, v42, v78
	v_add_f32_e32 v79, v43, v79
	v_add_f32_e32 v80, v44, v80
	v_add_f32_e32 v81, v45, v81
	ds_read_b128 v[42:45], v255 offset:160
	s_waitcnt lgkmcnt(0)
	v_add_f32_e32 v44, v40, v44
	v_mul_f32_e32 v40, 0xbfb8aa3b, v78
	v_exp_f32_e32 v40, v40
	v_add_f32_e32 v45, v41, v45
	v_add_f32_e32 v38, v38, v42
	v_add_f32_e32 v39, v39, v43
	v_add_f32_e32 v40, 1.0, v40
	s_nop 1
	v_mul_f32_e32 v38, 0xbfb8aa3b, v38
	v_mul_f32_e32 v39, 0xbfb8aa3b, v39
	v_exp_f32_e32 v38, v38
	s_nop 7
	v_mul_f32_e32 v42, 0xbfb8aa3b, v79
	v_exp_f32_e32 v42, v42
	v_exp_f32_e32 v39, v39
	v_add_f32_e32 v78, 1.0, v42
	s_nop 1
	s_nop 0
	s_nop 7
	v_pk_add_f32 v[42:43], v[38:39], 1.0 op_sel_hi:[1,0]
	s_nop 0
	s_nop 1
	s_nop 0
	s_nop 7
	v_rcp_f32_e32 v43, v43
	s_nop 0
	s_nop 7
	v_mul_f32_e32 v38, 0xbfb8aa3b, v80
	v_exp_f32_e32 v38, v38
	v_rcp_f32_e32 v42, v42
	s_nop 0
	v_add_f32_e32 v80, 1.0, v38
	s_nop 1
	s_nop 0
	s_nop 7
	v_mul_f32_e32 v38, 0xbfb8aa3b, v81
	v_exp_f32_e32 v38, v38
	s_nop 0
	v_add_f32_e32 v81, 1.0, v38
	s_nop 1
	s_nop 0
	s_nop 7
	v_rcp_f32_e32 v41, v40
	s_nop 0
	v_mul_f32_e32 v38, s45, v41
	v_rcp_f32_e32 v79, v78
	s_nop 0
	v_mul_f32_e32 v39, s45, v79
	v_rcp_f32_e32 v96, v80
	s_nop 0
	v_mul_f32_e32 v40, s45, v96
	v_rcp_f32_e32 v97, v81
	s_nop 0
	v_mul_f32_e32 v41, s45, v97
	v_mul_f32_e32 v38, 0x3fb8aa3b, v38
	v_mul_f32_e32 v39, 0x3fb8aa3b, v39
	v_mul_f32_e32 v40, 0x3fb8aa3b, v40
	v_mul_f32_e32 v41, 0x3fb8aa3b, v41
	v_exp_f32_e32 v38, v38
	v_exp_f32_e32 v39, v39
	v_exp_f32_e32 v40, v40
	v_exp_f32_e32 v41, v41
	global_store_dwordx4 v[94:95], v[38:41], off offset:128
	s_nop 1
	v_mul_f32_e32 v38, 0xbfb8aa3b, v44
	v_mul_f32_e32 v39, 0xbfb8aa3b, v45
	v_exp_f32_e32 v38, v38
	v_exp_f32_e32 v39, v39
	s_nop 0
	v_pk_add_f32 v[38:39], v[38:39], 1.0 op_sel_hi:[1,0]
	s_nop 0
	s_nop 1
	s_nop 0
	s_nop 7
	s_nop 0
	s_nop 7
	v_rcp_f32_e32 v45, v39
	s_nop 0
	v_rcp_f32_e32 v44, v38
	s_nop 0
	v_xor_b32_e32 v39, 0x80000000, v43
	v_xor_b32_e32 v38, 0x80000000, v42
	v_xor_b32_e32 v41, 0x80000000, v45
	v_xor_b32_e32 v40, 0x80000000, v44
	v_pk_mul_f32 v[40:41], v[72:73], v[40:41]
	v_pk_mul_f32 v[38:39], v[70:71], v[38:39]
	global_store_dwordx4 v[94:95], v[38:41], off offset:384
	s_nop 1
	v_pk_add_f32 v[38:39], v[42:43], -1.0 op_sel_hi:[1,0]
	v_pk_add_f32 v[40:41], v[44:45], -1.0 op_sel_hi:[1,0]
	v_pk_fma_f32 v[38:39], v[74:75], v[38:39], 1.0 op_sel_hi:[1,1,0]
	v_pk_fma_f32 v[40:41], v[76:77], v[40:41], 1.0 op_sel_hi:[1,1,0]
	v_pk_mul_f32 v[38:39], v[26:27], v[38:39]
	v_pk_mul_f32 v[40:41], v[28:29], v[40:41]
	global_store_dwordx4 v[94:95], v[38:41], off offset:640
	ds_read_b128 v[42:45], v255 offset:96
	s_waitcnt lgkmcnt(0)
	v_add_f32_e32 v42, v34, v42
	v_add_f32_e32 v43, v35, v43
	v_add_f32_e32 v44, v36, v44
	v_add_f32_e32 v45, v37, v45
	ds_read_b128 v[34:37], v255 offset:224
	s_waitcnt lgkmcnt(0)
	v_add_f32_e32 v30, v30, v34
	v_mul_f32_e32 v34, 0xbfb8aa3b, v42
	v_exp_f32_e32 v34, v34
	v_add_f32_e32 v31, v31, v35
	v_add_f32_e32 v32, v32, v36
	v_add_f32_e32 v33, v33, v37
	v_add_f32_e32 v42, 1.0, v34
	s_nop 1
	v_mul_f32_e32 v30, 0xbfb8aa3b, v30
	v_mul_f32_e32 v31, 0xbfb8aa3b, v31
	v_exp_f32_e32 v30, v30
	s_nop 7
	v_mul_f32_e32 v34, 0xbfb8aa3b, v43
	v_exp_f32_e32 v34, v34
	v_exp_f32_e32 v31, v31
	v_mul_f32_e32 v32, 0xbfb8aa3b, v32
	v_mul_f32_e32 v33, 0xbfb8aa3b, v33
	v_add_f32_e32 v43, 1.0, v34
	s_nop 1
	v_pk_add_f32 v[30:31], v[30:31], 1.0 op_sel_hi:[1,0]
	v_exp_f32_e32 v32, v32
	v_exp_f32_e32 v33, v33
	s_nop 7
	v_pk_add_f32 v[32:33], v[32:33], 1.0 op_sel_hi:[1,0]
	s_nop 7
	v_rcp_f32_e32 v31, v31
	s_nop 0
	v_mul_f32_e32 v34, 0xbfb8aa3b, v44
	v_exp_f32_e32 v34, v34
	s_nop 6
	v_add_f32_e32 v44, 1.0, v34
	s_nop 1
	v_rcp_f32_e32 v30, v30
	s_nop 0
	s_nop 0
	s_nop 0
	s_nop 7
	v_mul_f32_e32 v34, 0xbfb8aa3b, v45
	v_exp_f32_e32 v34, v34
	s_nop 0
	v_add_f32_e32 v45, 1.0, v34
	s_nop 1
	s_nop 0
	s_nop 7
	s_nop 0
	s_nop 7
	v_rcp_f32_e32 v33, v33
	s_nop 0
	s_nop 7
	v_rcp_f32_e32 v32, v32
	s_nop 0
	v_pk_add_f32 v[34:35], v[30:31], -1.0 op_sel_hi:[1,0]
	v_pk_add_f32 v[36:37], v[32:33], -1.0 op_sel_hi:[1,0]
	v_pk_fma_f32 v[34:35], v[74:75], v[34:35], 1.0 op_sel_hi:[1,1,0]
	v_pk_fma_f32 v[36:37], v[76:77], v[36:37], 1.0 op_sel_hi:[1,1,0]
	v_pk_mul_f32 v[74:75], v[26:27], v[34:35]
	v_pk_mul_f32 v[76:77], v[28:29], v[36:37]
	v_xor_b32_e32 v27, 0x80000000, v31
	v_xor_b32_e32 v26, 0x80000000, v30
	v_xor_b32_e32 v29, 0x80000000, v33
	v_xor_b32_e32 v28, 0x80000000, v32
	v_rcp_f32_e32 v78, v42
	s_nop 0
	v_mul_f32_e32 v30, s45, v78
	v_rcp_f32_e32 v79, v43
	s_nop 0
	v_mul_f32_e32 v31, s45, v79
	v_rcp_f32_e32 v80, v44
	s_nop 0
	v_mul_f32_e32 v32, s45, v80
	v_rcp_f32_e32 v81, v45
	s_nop 0
	v_mul_f32_e32 v33, s45, v81
	v_mul_f32_e32 v30, 0x3fb8aa3b, v30
	v_mul_f32_e32 v31, 0x3fb8aa3b, v31
	v_mul_f32_e32 v32, 0x3fb8aa3b, v32
	v_mul_f32_e32 v33, 0x3fb8aa3b, v33
	v_exp_f32_e32 v30, v30
	v_exp_f32_e32 v31, v31
	v_exp_f32_e32 v32, v32
	v_exp_f32_e32 v33, v33
	v_pk_mul_f32 v[28:29], v[72:73], v[28:29]
	v_pk_mul_f32 v[26:27], v[70:71], v[26:27]
	global_store_dwordx4 v[82:83], v[30:33], off offset:128
	global_store_dwordx4 v[82:83], v[26:29], off offset:384
	global_store_dwordx4 v[82:83], v[74:77], off offset:640
	v_lshl_add_u64 v[30:31], v[172:173], 2, v[190:191]
	global_load_dwordx4 v[70:73], v[30:31], off
	s_nop 0
	global_load_dwordx4 v[30:33], v[188:189], off offset:2240
	flat_load_dwordx4 v[42:45], v[174:175] offset:192
	flat_load_dwordx4 v[34:37], v[176:177] offset:192
	v_pk_mul_f32 v[28:29], v[192:193], v[130:131] op_sel_hi:[1,0]
	v_pk_mul_f32 v[26:27], v[194:195], v[130:131] op_sel_hi:[1,0]
	s_waitcnt vmcnt(0)
	global_store_dwordx4 v[186:187], v[70:73], off offset:704
	global_store_dwordx4 v[186:187], v[30:33], off offset:192
	global_store_dwordx4 v[186:187], v[26:29], off offset:448
	ds_read_b128 v[70:73], v255 offset:48
	s_waitcnt lgkmcnt(0)
	v_add_f32_e32 v70, v18, v70
	v_add_f32_e32 v71, v19, v71
	v_add_f32_e32 v72, v20, v72
	v_add_f32_e32 v73, v21, v73
	ds_read_b128 v[18:21], v255 offset:176
	s_waitcnt lgkmcnt(0)
	v_add_f32_e32 v15, v15, v19
	v_add_f32_e32 v19, v16, v20
	v_mul_f32_e32 v16, 0xbfb8aa3b, v70
	v_exp_f32_e32 v16, v16
	v_add_f32_e32 v78, v17, v21
	v_add_f32_e32 v14, v14, v18
	v_fma_f32 v18, v22, v84, 0
	v_add_f32_e32 v16, 1.0, v16
	s_nop 1
	v_fmac_f32_e32 v18, v23, v85
	v_fmac_f32_e32 v18, v24, v86
	v_fmac_f32_e32 v18, v25, v87
	s_nop 2
	v_fmac_f32_e32 v18, v22, v88
	s_nop 0
	v_fmac_f32_e32 v18, v23, v89
	s_nop 3
	v_mul_f32_e32 v20, 0xbfb8aa3b, v71
	v_exp_f32_e32 v20, v20
	v_mul_f32_e32 v14, 0xbfb8aa3b, v14
	v_mul_f32_e32 v15, 0xbfb8aa3b, v15
	v_fmac_f32_e32 v18, v24, v90
	v_add_f32_e32 v22, 1.0, v20
	s_nop 1
	v_exp_f32_e32 v14, v14
	v_exp_f32_e32 v15, v15
	v_fmac_f32_e32 v18, v25, v91
	s_nop 7
	v_pk_add_f32 v[20:21], v[14:15], 1.0 op_sel_hi:[1,0]
	s_nop 0
	s_nop 1
	s_nop 0
	s_nop 7
	v_rcp_f32_e32 v21, v21
	s_nop 0
	s_nop 7
	v_mul_f32_e32 v14, 0xbfb8aa3b, v72
	v_exp_f32_e32 v14, v14
	v_rcp_f32_e32 v20, v20
	s_nop 0
	v_add_f32_e32 v70, 1.0, v14
	s_nop 1
	s_nop 0
	s_nop 7
	v_mul_f32_e32 v14, 0xbfb8aa3b, v73
	v_exp_f32_e32 v14, v14
	s_nop 0
	v_add_f32_e32 v72, 1.0, v14
	s_nop 1
	s_nop 0
	s_nop 7
	v_rcp_f32_e32 v17, v16
	s_nop 0
	v_mul_f32_e32 v14, s45, v17
	v_rcp_f32_e32 v23, v22
	s_nop 0
	v_mul_f32_e32 v15, s45, v23
	v_rcp_f32_e32 v71, v70
	s_nop 0
	v_mul_f32_e32 v16, s45, v71
	v_rcp_f32_e32 v73, v72
	s_nop 0
	v_mul_f32_e32 v17, s45, v73
	v_mul_f32_e32 v14, 0x3fb8aa3b, v14
	v_mul_f32_e32 v15, 0x3fb8aa3b, v15
	v_mul_f32_e32 v16, 0x3fb8aa3b, v16
	v_mul_f32_e32 v17, 0x3fb8aa3b, v17
	v_exp_f32_e32 v14, v14
	v_exp_f32_e32 v15, v15
	v_exp_f32_e32 v16, v16
	v_exp_f32_e32 v17, v17
	global_store_dwordx4 v[94:95], v[14:17], off offset:192
	s_nop 1
	v_mul_f32_e32 v14, 0xbfb8aa3b, v19
	v_mul_f32_e32 v15, 0xbfb8aa3b, v78
	v_exp_f32_e32 v14, v14
	v_exp_f32_e32 v15, v15
	s_nop 0
	v_pk_add_f32 v[14:15], v[14:15], 1.0 op_sel_hi:[1,0]
	s_nop 0
	s_nop 1
	s_nop 0
	s_nop 7
	s_nop 0
	s_nop 7
	v_rcp_f32_e32 v23, v15
	s_nop 0
	v_rcp_f32_e32 v22, v14
	s_nop 0
	v_xor_b32_e32 v15, 0x80000000, v21
	v_xor_b32_e32 v14, 0x80000000, v20
	v_xor_b32_e32 v17, 0x80000000, v23
	v_xor_b32_e32 v16, 0x80000000, v22
	v_pk_mul_f32 v[16:17], v[28:29], v[16:17]
	v_pk_mul_f32 v[14:15], v[26:27], v[14:15]
	global_store_dwordx4 v[94:95], v[14:17], off offset:448
	v_mul_f32_e32 v19, v46, v66
	v_fmac_f32_e32 v18, v50, v19
	v_pk_add_f32 v[14:15], v[20:21], -1.0 op_sel_hi:[1,0]
	v_mul_f32_e32 v19, v47, v67
	v_pk_fma_f32 v[14:15], v[42:43], v[14:15], 1.0 op_sel_hi:[1,1,0]
	v_fmac_f32_e32 v18, v51, v19
	v_pk_mul_f32 v[20:21], v[10:11], v[14:15]
	v_pk_add_f32 v[14:15], v[22:23], -1.0 op_sel_hi:[1,0]
	v_mul_f32_e32 v19, v48, v68
	v_pk_fma_f32 v[14:15], v[44:45], v[14:15], 1.0 op_sel_hi:[1,1,0]
	v_fmac_f32_e32 v18, v52, v19
	v_pk_mul_f32 v[22:23], v[12:13], v[14:15]
	global_store_dwordx4 v[94:95], v[20:23], off offset:704
	ds_read_b128 v[14:17], v255 offset:112
	v_mul_f32_e32 v19, v49, v69
	ds_read_b128 v[66:69], v255 offset:240
	v_fmac_f32_e32 v18, v53, v19
	v_mul_f32_e32 v19, v46, v54
	v_fmac_f32_e32 v18, v50, v19
	v_mul_f32_e32 v19, v47, v55
	v_fmac_f32_e32 v18, v51, v19
	v_mul_f32_e32 v19, v48, v56
	v_fmac_f32_e32 v18, v52, v19
	v_mul_f32_e32 v19, v49, v57
	v_fmac_f32_e32 v18, v53, v19
	v_mul_f32_e32 v19, v58, v38
	v_fmac_f32_e32 v18, v62, v19
	v_mul_f32_e32 v19, v59, v39
	v_fmac_f32_e32 v18, v63, v19
	v_mul_f32_e32 v19, v60, v40
	v_fmac_f32_e32 v18, v64, v19
	v_mul_f32_e32 v19, v61, v41
	v_fmac_f32_e32 v18, v65, v19
	v_mul_f32_e32 v19, v58, v74
	v_fmac_f32_e32 v18, v62, v19
	v_mul_f32_e32 v19, v59, v75
	v_fmac_f32_e32 v18, v63, v19
	v_mul_f32_e32 v19, v60, v76
	v_fmac_f32_e32 v18, v64, v19
	v_mul_f32_e32 v19, v61, v77
	v_fmac_f32_e32 v18, v65, v19
	v_mul_f32_e32 v19, v30, v20
	v_fmac_f32_e32 v18, v34, v19
	s_waitcnt lgkmcnt(0)
	v_add_f32_e32 v2, v2, v14
	v_mul_f32_e32 v2, 0xbfb8aa3b, v2
	v_exp_f32_e32 v2, v2
	v_mul_f32_e32 v14, v31, v21
	v_fmac_f32_e32 v18, v35, v14
	v_mul_f32_e32 v14, v32, v22
	v_add_f32_e32 v2, 1.0, v2
	s_nop 1
	v_add_f32_e32 v3, v3, v15
	v_fmac_f32_e32 v18, v36, v14
	v_mul_f32_e32 v14, v33, v23
	v_mul_f32_e32 v3, 0xbfb8aa3b, v3
	v_fmac_f32_e32 v18, v37, v14
	s_nop 0
	v_exp_f32_e32 v3, v3
	s_nop 4
	v_add_f32_e32 v15, 1.0, v3
	s_nop 0
	v_div_scale_f32 v19, s[10:11], v15, v15, s45
	s_nop 0
	v_rcp_f32_e32 v20, v19
	v_rcp_f32_e32 v14, v2
	s_nop 0
	v_mul_f32_e32 v2, s45, v14
	v_mul_f32_e32 v2, 0x3fb8aa3b, v2
	v_exp_f32_e32 v14, v2
	v_fma_f32 v3, -v19, v20, 1.0
	v_add_f32_e32 v2, v6, v66
	v_fmac_f32_e32 v20, v3, v20
	v_div_scale_f32 v6, vcc, s45, v15, s45
	v_mul_f32_e32 v21, v6, v20
	v_fma_f32 v3, -v19, v21, v6
	v_fmac_f32_e32 v21, v3, v20
	v_add_f32_e32 v3, v7, v67
	v_mul_f32_e32 v2, 0xbfb8aa3b, v2
	v_mul_f32_e32 v3, 0xbfb8aa3b, v3
	v_exp_f32_e32 v2, v2
	v_exp_f32_e32 v3, v3
	v_fma_f32 v6, -v19, v21, v6
	v_div_fmas_f32 v6, v6, v20, v21
	v_div_fixup_f32 v6, v6, v15, s45
	v_pk_add_f32 v[2:3], v[2:3], 1.0 op_sel_hi:[1,0]
	v_mul_f32_e32 v6, 0x3fb8aa3b, v6
	s_nop 1
	v_exp_f32_e32 v15, v6
	v_add_f32_e32 v4, v4, v16
	v_mul_f32_e32 v4, 0xbfb8aa3b, v4
	s_nop 7
	v_rcp_f32_e32 v3, v3
	s_nop 0
	v_exp_f32_e32 v4, v4
	s_nop 7
	v_rcp_f32_e32 v2, v2
	s_nop 0
	v_pk_add_f32 v[6:7], v[2:3], -1.0 op_sel_hi:[1,0]
	v_add_f32_e32 v4, 1.0, v4
	v_pk_fma_f32 v[6:7], v[42:43], v[6:7], 1.0 op_sel_hi:[1,1,0]
	v_add_f32_e32 v5, v5, v17
	v_pk_mul_f32 v[6:7], v[10:11], v[6:7]
	s_nop 1
	v_mul_f32_e32 v10, v30, v6
	v_fmac_f32_e32 v18, v34, v10
	v_mul_f32_e32 v10, v31, v7
	v_fmac_f32_e32 v18, v35, v10
	s_nop 3
	v_mul_f32_e32 v5, 0xbfb8aa3b, v5
	s_nop 0
	v_exp_f32_e32 v5, v5
	s_nop 2
	v_rcp_f32_e32 v10, v4
	s_nop 0
	v_mul_f32_e32 v4, s45, v10
	v_add_f32_e32 v10, 1.0, v5
	v_div_scale_f32 v11, s[10:11], v10, v10, s45
	v_rcp_f32_e32 v17, v11
	v_mul_f32_e32 v4, 0x3fb8aa3b, v4
	v_exp_f32_e32 v16, v4
	v_add_f32_e32 v4, v8, v68
	v_fma_f32 v5, -v11, v17, 1.0
	v_fmac_f32_e32 v17, v5, v17
	v_div_scale_f32 v8, vcc, s45, v10, s45
	v_mul_f32_e32 v19, v8, v17
	v_fma_f32 v5, -v11, v19, v8
	v_fmac_f32_e32 v19, v5, v17
	v_add_f32_e32 v5, v9, v69
	v_mul_f32_e32 v4, 0xbfb8aa3b, v4
	v_mul_f32_e32 v5, 0xbfb8aa3b, v5
	v_exp_f32_e32 v4, v4
	v_exp_f32_e32 v5, v5
	v_fma_f32 v8, -v11, v19, v8
	v_div_fmas_f32 v8, v8, v17, v19
	v_div_fixup_f32 v8, v8, v10, s45
	v_pk_add_f32 v[4:5], v[4:5], 1.0 op_sel_hi:[1,0]
	v_mul_f32_e32 v8, 0x3fb8aa3b, v8
	s_nop 1
	v_exp_f32_e32 v17, v8
	s_nop 7
	v_rcp_f32_e32 v5, v5
	s_nop 0
	s_nop 7
	v_rcp_f32_e32 v4, v4
	s_nop 0
	v_pk_add_f32 v[8:9], v[4:5], -1.0 op_sel_hi:[1,0]
	v_xor_b32_e32 v11, 0x80000000, v3
	v_pk_fma_f32 v[8:9], v[44:45], v[8:9], 1.0 op_sel_hi:[1,1,0]
	s_nop 0
	v_pk_mul_f32 v[8:9], v[12:13], v[8:9]
	s_nop 0
	v_mul_f32_e32 v10, v32, v8
	v_fmac_f32_e32 v18, v36, v10
	v_mul_f32_e32 v3, v33, v9
	v_fmac_f32_e32 v18, v37, v3
	ds_bpermute_b32 v19, v244, v18
	v_xor_b32_e32 v10, 0x80000000, v2
	v_xor_b32_e32 v3, 0x80000000, v5
	v_xor_b32_e32 v2, 0x80000000, v4
	v_pk_mul_f32 v[12:13], v[28:29], v[2:3]
	s_waitcnt lgkmcnt(0)
	v_add_f32_e32 v2, v18, v19
	ds_bpermute_b32 v3, v245, v2
	v_pk_mul_f32 v[10:11], v[26:27], v[10:11]
	global_store_dwordx4 v[82:83], v[14:17], off offset:192
	global_store_dwordx4 v[82:83], v[10:13], off offset:448
	global_store_dwordx4 v[82:83], v[6:9], off offset:704
	s_and_saveexec_b64 s[10:11], s[6:7]
	s_cbranch_execz .LBB0_473
	s_waitcnt lgkmcnt(0)
	v_add_f32_e32 v4, v2, v3
	v_lshl_add_u32 v2, v243, 2, v98
	v_ashrrev_i32_e32 v3, 31, v2
	v_lshl_add_u64 v[2:3], v[2:3], 2, s[52:53]
	global_store_dword v[2:3], v4, off
	s_branch .LBB0_473
